# speedup vs baseline: 1.0016x; 1.0016x over previous
.LBB0_141:
	v_cvt_pk_bf16_f32 v2, v110, v111
	v_cvt_pk_bf16_f32 v3, v108, v109
	ds_write2st64_b32 v154, v2, v3 offset0:128 offset1:129
	v_cvt_pk_bf16_f32 v2, v106, v107
	v_cvt_pk_bf16_f32 v3, v104, v105
	ds_write2st64_b32 v154, v2, v3 offset0:130 offset1:131
	v_cvt_pk_bf16_f32 v2, v102, v103
	v_cvt_pk_bf16_f32 v3, v100, v101
	ds_write2st64_b32 v154, v2, v3 offset0:132 offset1:133
	v_cvt_pk_bf16_f32 v2, v98, v99
	v_cvt_pk_bf16_f32 v3, v96, v97
	v_ashrrev_i32_e32 v95, 31, v226
	v_mov_b32_e32 v94, v226
	ds_write2st64_b32 v154, v2, v3 offset0:134 offset1:135
	v_lshlrev_b64 v[2:3], 11, v[94:95]
	v_lshl_add_u64 v[2:3], v[90:91], 0, v[2:3]
	global_load_dwordx4 v[38:41], v[2:3], off offset:48
	global_load_dwordx4 v[46:49], v[2:3], off offset:32
	global_load_dwordx4 v[50:53], v[2:3], off offset:16
	global_load_dwordx4 v[54:57], v[2:3], off
	global_load_dwordx4 v[26:29], v[2:3], off offset:1072
	global_load_dwordx4 v[30:33], v[2:3], off offset:1056
	global_load_dwordx4 v[34:37], v[2:3], off offset:1040
	global_load_dwordx4 v[42:45], v[2:3], off offset:1024
	s_setprio 3
	v_lshlrev_b32_e32 v61, 2, v180
	v_sub_u32_e32 v58, v154, v61
	v_and_b32_e32 v61, 1, v83
	v_lshl_add_u32 v58, v61, 10, v58
	v_lshrrev_b32_e32 v61, 2, v83
	v_lshl_add_u32 v58, v61, 8, v58
	v_lshrrev_b32_e32 v61, 4, v180
	v_lshl_add_u32 v58, v61, 4, v58
	v_and_b32_e32 v59, 7, v83
	v_xor_b32_e32 v59, v59, v61
	v_lshlrev_b32_e32 v59, 4, v59
	v_lshl_add_u32 v59, v83, 7, v59
	v_xor_b32_e32 v60, 64, v59
	ds_read_b128 v[62:65], v58 offset:32768
	ds_read_b128 v[66:69], v58 offset:32832
	ds_read_b128 v[70:73], v58 offset:32896
	ds_read_b128 v[74:77], v58 offset:32960
	ds_read_b128 v[78:81], v59 offset:0
	ds_read_b128 v[196:199], v60 offset:0
	ds_read_b128 v[230:233], v59 offset:2048
	ds_read_b128 v[234:237], v60 offset:2048
	s_waitcnt lgkmcnt(2)
	v_mfma_f32_16x16x32_bf16 v[112:115], v[62:65], v[78:81], 0
	v_mfma_f32_16x16x32_bf16 v[112:115], v[66:69], v[196:199], v[112:115]
	ds_read_b128 v[78:81], v59 offset:4096
	ds_read_b128 v[196:199], v60 offset:4096
	s_waitcnt lgkmcnt(2)
	v_mfma_f32_16x16x32_bf16 v[116:119], v[62:65], v[230:233], 0
	v_mfma_f32_16x16x32_bf16 v[116:119], v[66:69], v[234:237], v[116:119]
	ds_read_b128 v[230:233], v59 offset:6144
	ds_read_b128 v[234:237], v60 offset:6144
	s_waitcnt lgkmcnt(2)
	v_mfma_f32_16x16x32_bf16 v[120:123], v[62:65], v[78:81], 0
	v_mfma_f32_16x16x32_bf16 v[120:123], v[66:69], v[196:199], v[120:123]
	ds_read_b128 v[78:81], v59 offset:8192
	ds_read_b128 v[196:199], v60 offset:8192
	s_waitcnt lgkmcnt(2)
	v_mfma_f32_16x16x32_bf16 v[126:129], v[62:65], v[230:233], 0
	v_mfma_f32_16x16x32_bf16 v[126:129], v[66:69], v[234:237], v[126:129]
	ds_read_b128 v[230:233], v59 offset:10240
	ds_read_b128 v[234:237], v60 offset:10240
	s_waitcnt lgkmcnt(2)
	v_mfma_f32_16x16x32_bf16 v[130:133], v[62:65], v[78:81], 0
	v_mfma_f32_16x16x32_bf16 v[130:133], v[66:69], v[196:199], v[130:133]
	ds_read_b128 v[78:81], v59 offset:12288
	ds_read_b128 v[196:199], v60 offset:12288
	s_waitcnt lgkmcnt(2)
	v_mfma_f32_16x16x32_bf16 v[134:137], v[62:65], v[230:233], 0
	v_mfma_f32_16x16x32_bf16 v[134:137], v[66:69], v[234:237], v[134:137]
	ds_read_b128 v[230:233], v59 offset:14336
	ds_read_b128 v[234:237], v60 offset:14336
	s_waitcnt lgkmcnt(2)
	v_mfma_f32_16x16x32_bf16 v[138:141], v[62:65], v[78:81], 0
	v_mfma_f32_16x16x32_bf16 v[138:141], v[66:69], v[196:199], v[138:141]
	ds_read_b128 v[78:81], v59 offset:16384
	ds_read_b128 v[196:199], v60 offset:16384
	s_waitcnt lgkmcnt(2)
	v_mfma_f32_16x16x32_bf16 v[142:145], v[62:65], v[230:233], 0
	v_mfma_f32_16x16x32_bf16 v[142:145], v[66:69], v[234:237], v[142:145]
	ds_read_b128 v[230:233], v59 offset:18432
	ds_read_b128 v[234:237], v60 offset:18432
	s_waitcnt lgkmcnt(2)
	v_mfma_f32_16x16x32_bf16 v[146:149], v[70:73], v[78:81], 0
	v_mfma_f32_16x16x32_bf16 v[146:149], v[74:77], v[196:199], v[146:149]
	ds_read_b128 v[78:81], v59 offset:20480
	ds_read_b128 v[196:199], v60 offset:20480
	s_waitcnt lgkmcnt(2)
	v_mfma_f32_16x16x32_bf16 v[150:153], v[70:73], v[230:233], 0
	v_mfma_f32_16x16x32_bf16 v[150:153], v[74:77], v[234:237], v[150:153]
	ds_read_b128 v[230:233], v59 offset:22528
	ds_read_b128 v[234:237], v60 offset:22528
	s_waitcnt lgkmcnt(2)
	v_mfma_f32_16x16x32_bf16 v[98:101], v[70:73], v[78:81], 0
	v_mfma_f32_16x16x32_bf16 v[98:101], v[74:77], v[196:199], v[98:101]
	ds_read_b128 v[78:81], v59 offset:24576
	ds_read_b128 v[196:199], v60 offset:24576
	s_waitcnt lgkmcnt(2)
	v_mfma_f32_16x16x32_bf16 v[102:105], v[70:73], v[230:233], 0
	v_mfma_f32_16x16x32_bf16 v[102:105], v[74:77], v[234:237], v[102:105]
	ds_read_b128 v[230:233], v59 offset:26624
	ds_read_b128 v[234:237], v60 offset:26624
	s_waitcnt lgkmcnt(2)
	v_mfma_f32_16x16x32_bf16 v[106:109], v[70:73], v[78:81], 0
	v_mfma_f32_16x16x32_bf16 v[106:109], v[74:77], v[196:199], v[106:109]
	ds_read_b128 v[78:81], v59 offset:28672
	ds_read_b128 v[196:199], v60 offset:28672
	s_waitcnt lgkmcnt(2)
	v_mfma_f32_16x16x32_bf16 v[238:241], v[70:73], v[230:233], 0
	v_mfma_f32_16x16x32_bf16 v[238:241], v[74:77], v[234:237], v[238:241]
	ds_read_b128 v[230:233], v59 offset:30720
	ds_read_b128 v[234:237], v60 offset:30720
	s_waitcnt lgkmcnt(2)
	v_mfma_f32_16x16x32_bf16 v[242:245], v[70:73], v[78:81], 0
	v_mfma_f32_16x16x32_bf16 v[242:245], v[74:77], v[196:199], v[242:245]
	s_waitcnt lgkmcnt(0)
	v_mfma_f32_16x16x32_bf16 v[246:249], v[70:73], v[230:233], 0
	v_mfma_f32_16x16x32_bf16 v[246:249], v[74:77], v[234:237], v[246:249]
	s_setprio 0
	s_mov_b32 s0, 0
	s_mov_b64 s[6:7], -1
